# attn loop without dummy-destination selects (last-step DMA skipped, drain at loop exit) + counter barrier for prologue sync + paired table reads
# speedup vs baseline: 1.0044x; 1.0034x over previous
; #define SBAR() __builtin_amdgcn_sched_barrier(0)
; #define WAIT_BAR(N) asm volatile("s_waitcnt vmcnt(" #N ") lgkmcnt(0)\n\ts_barrier":::"memory")
;   #define VRK(dst,vp_,ks_) do{ _Pragma("unroll") for(int d0_=0;d0_<4;++d0_){ dst[d0_]=*(const __attribute__((address_space(3))) bf16x8*)((vp_)+d0_*4096+(ks_)*1024); } }while(0)
; template<int THRL> __device__ __forceinline__ void attn_unit(int b,int h,int qb,const AttnArgs&A,char*shm,bool setup){
;     ...
;     WAIT_BAR(4);
;     const int kv0=t*KVBLK;
;     const bool act=(kv0<=qw0+QBLK-1);
;     const bool actn=(t+1<NT)&&(kv0+KVBLK<=qw0+QBLK-1);
;     const lds_cptr vp=vp0+vs_t;
;     const bool dk=(t+3<NT), dv=(t+2<NT);
;     const unsigned char*gk_=imgS+((size_t)(dk?t+3:NT-1)<<15); const unsigned char*gv_=imgS+((size_t)(dv?t+2:NT-1)<<15)+16384;
;     const unsigned kd_=(unsigned)__builtin_amdgcn_readfirstlane(dk?kdst+ks_t:ddst), vd_=(unsigned)__builtin_amdgcn_readfirstlane(dv?vdst+vs_nn:ddst);
;     if(act){
;       VRK(va,vp,0); VRK(vb,vp,1);
;       SBAR();
;       QKM(cini);
;     }
;     if(act){
;       const bool far=(qw0-(kv0+63)>=113);
;       if(!far){ const float*bt=biasT+mp*128; const int dq=qpos-kv0-4*hi;
;         #pragma unroll
;         for(int r=0;r<16;++r){ const int d=dq-((r&3)+8*(r>>2));
;           const int i0=d<0?0:(d>127?127:d);
;           const float b0=bt[i0];
;           const float n0=d>=0?0.f:-INFINITY;
;           p0[r]=(p0[r]+(b0-cfar))+n0; if((r&7)==7)asm volatile("":::"memory"); }
;         #pragma unroll
;         for(int r=0;r<16;++r){ const int d1=dq-32-((r&3)+8*(r>>2));
;           const int i1=d1<0?0:(d1>127?127:d1);
;           const float b1=bt[i1];
;           const float n1=d1>=0?0.f:-INFINITY;
;           p1[r]=(p1[r]+(b1-cfar))+n1; if((r&7)==7)asm volatile("":::"memory"); } }
.LBB0_243:
	s_add_i32 s95, s41, 1
	s_add_i32 s82, s94, s46
	s_add_i32 s73, s9, s99
	s_waitcnt vmcnt(4) lgkmcnt(0)
	s_barrier
	s_cmp_lt_i32 s22, 0xffffffa2
	s_cbranch_scc1 .Ltr_inact
	v_add_u32_e32 v15, s94, v210
	ds_read_b128 v[162:165], v15 offset:49152
	ds_read_b128 v[146:149], v15 offset:50176
	ds_read_b128 v[158:161], v15 offset:53248
	ds_read_b128 v[10:13], v15 offset:54272
	ds_read_b128 v[154:157], v15 offset:57344
	ds_read_b128 v[6:9], v15 offset:58368
	ds_read_b128 v[150:153], v15 offset:61440
	ds_read_b128 v[2:5], v15 offset:62464
	v_mfma_f32_32x32x16_bf16 v[114:129], v[178:181], v[130:133], v[82:97]
	s_cmpk_gt_i32 s22, 0x70
	v_mfma_f32_32x32x16_bf16 v[98:113], v[182:185], v[130:133], v[82:97]
	v_mfma_f32_32x32x16_bf16 v[98:113], v[186:189], v[134:137], v[98:113]
	v_mfma_f32_32x32x16_bf16 v[114:129], v[166:169], v[134:137], v[114:129]
	v_mfma_f32_32x32x16_bf16 v[98:113], v[190:193], v[138:141], v[98:113]
	v_mfma_f32_32x32x16_bf16 v[114:129], v[174:177], v[138:141], v[114:129]
	v_mfma_f32_32x32x16_bf16 v[98:113], v[194:197], v[142:145], v[98:113]
	v_mfma_f32_32x32x16_bf16 v[114:129], v[170:173], v[142:145], v[114:129]
	s_cbranch_scc1 .LBB0_246
	v_lshlrev_b32_e32 v212, 2, v206
	v_sub_u32_e32 v212, v208, v212
	v_add_u32_e32 v212, s22, v212
	s_sub_i32 s20, s29, 0x18800
	s_lshl_b32 s20, s20, 1
	s_add_i32 s20, s20, 0x1d000
	v_lshl_add_u32 v213, v212, 2, s20
	ds_read2_b32 v[166:167], v213 offset0:126 offset1:125
	ds_read2_b32 v[168:169], v213 offset0:124 offset1:123
	ds_read2_b32 v[170:171], v213 offset0:118 offset1:117
	ds_read2_b32 v[172:173], v213 offset0:116 offset1:115
	ds_read2_b32 v[174:175], v213 offset0:110 offset1:109
	ds_read2_b32 v[176:177], v213 offset0:108 offset1:107
	ds_read2_b32 v[178:179], v213 offset0:102 offset1:101
	ds_read2_b32 v[180:181], v213 offset0:100 offset1:99
	ds_read2_b32 v[182:183], v213 offset0:94 offset1:93
	ds_read2_b32 v[184:185], v213 offset0:92 offset1:91
	ds_read2_b32 v[186:187], v213 offset0:86 offset1:85
	ds_read2_b32 v[188:189], v213 offset0:84 offset1:83
	ds_read2_b32 v[190:191], v213 offset0:78 offset1:77
	ds_read2_b32 v[192:193], v213 offset0:76 offset1:75
	ds_read2_b32 v[194:195], v213 offset0:70 offset1:69
	ds_read2_b32 v[196:197], v213 offset0:68 offset1:67
	s_waitcnt lgkmcnt(8)
	v_pk_add_f32 v[114:115], v[114:115], v[166:167]
	v_pk_add_f32 v[116:117], v[116:117], v[168:169]
	v_pk_add_f32 v[118:119], v[118:119], v[170:171]
	v_pk_add_f32 v[120:121], v[120:121], v[172:173]
	v_pk_add_f32 v[122:123], v[122:123], v[174:175]
	v_pk_add_f32 v[124:125], v[124:125], v[176:177]
	v_pk_add_f32 v[126:127], v[126:127], v[178:179]
	v_pk_add_f32 v[128:129], v[128:129], v[180:181]
	s_waitcnt lgkmcnt(0)
	v_pk_add_f32 v[98:99], v[98:99], v[182:183]
	v_pk_add_f32 v[100:101], v[100:101], v[184:185]
	v_pk_add_f32 v[102:103], v[102:103], v[186:187]
	v_pk_add_f32 v[104:105], v[104:105], v[188:189]
	v_pk_add_f32 v[106:107], v[106:107], v[190:191]
	v_pk_add_f32 v[108:109], v[108:109], v[192:193]
	v_pk_add_f32 v[110:111], v[110:111], v[194:195]
	v_pk_add_f32 v[112:113], v[112:113], v[196:197]

; template<int THRL> __device__ __forceinline__ void attn_unit(int b,int h,int qb,const AttnArgs&A,char*shm,bool setup){
;     ...
;     glds16s(gk_,voff,kd_); glds16s(gk_+8192,voff,kd_+8192); glds16s(gv_,voff,vd_); glds16s(gv_+8192,voff,vd_+8192);
;     ks_t=ks_n; ks_n=(ks_n==2*SLOT16)?0:ks_n+SLOT16; vs_t=(vs_t==2*SLOT16)?0:vs_t+SLOT16; vs_nn=(vs_nn==2*SLOT16)?0:vs_nn+SLOT16;
;   }
.LBB0_249:
	s_add_i32 s41, s41, 1
	s_cmp_lg_u32 s41, s8
	s_cbranch_scc0 .Lloop_exit
	s_mov_b32 m0, s82
	s_nop 0
	global_load_lds_dwordx4 v209, s[20:21]
	s_mov_b32 m0, s83
	s_sub_i32 s22, s22, 64
	global_load_lds_dwordx4 v14, s[20:21]
	s_mov_b32 m0, s73
	s_mov_b32 s83, s94
	global_load_lds_dwordx4 v209, s[84:85]
	s_mov_b32 m0, s95
	s_mov_b32 s94, s23
	global_load_lds_dwordx4 v14, s[84:85]
	s_mov_b32 s23, s9
	s_mov_b32 s9, s83
	s_branch .LBB0_243
.Lloop_exit:
	s_waitcnt vmcnt(0)
	s_branch .LBB0_252
